# seams: early L2 write-back started by the third-to-last arriver on the XCD instead of the second-to-last
# speedup vs baseline: 1.0183x; 1.0183x over previous
; __device__ __forceinline__ unsigned xb_ld(unsigned* p)              { return __hip_atomic_load(p, __ATOMIC_RELAXED, __HIP_MEMORY_SCOPE_AGENT); }
; __device__ __forceinline__ unsigned xb_add(unsigned* p, unsigned v) { return __hip_atomic_fetch_add(p, v, __ATOMIC_RELAXED, __HIP_MEMORY_SCOPE_AGENT); }
; #define XB_SPIN(cond, bar) do { unsigned _sp = 0; while (cond) { __builtin_amdgcn_s_sleep(1); \
;     if ((++_sp & 255u) == 0u) { if (xb_ld(&(bar)[XB_TMO])) break; if (_sp > XB_SPIN_CAP) { atomicAdd(&(bar)[XB_TMO], 1u); break; } } } } while (0)
; __device__ __forceinline__ void xcd_barrier(const XcdBarrier& b, const int wv) {
;     ...
;         unsigned nloc = b.st[0], nx = b.st[1];
;         if (nloc == 0u) { xcd_barrier_complete(bar, b.x, nloc, nx); b.st[0] = nloc; b.st[1] = nx; }
;         const unsigned old = xb_add(&bar[XB_XSUB(b.x)], 1u);
;         const unsigned gen = old / nloc;
;         if (old + 1u == (gen + 1u) * nloc) {
;             __builtin_amdgcn_fence(__ATOMIC_RELEASE, "agent");
;             asm volatile("s_waitcnt vmcnt(0)" ::: "memory");
;             const unsigned og = xb_add(&bar[XB_TOP], 1u);
;             const unsigned tg = og / nx;
;             if (og + 1u == (tg + 1u) * nx) xb_add(&bar[XB_TOPGEN], 1u);
;             else XB_SPIN(xb_ld(&bar[XB_TOPGEN]) == tg, bar);
.Lseam1_328:
	s_or_b64 exec, exec, s[14:15]
	v_cvt_f32_u32_e32 v4, v2
	s_waitcnt vmcnt(0)
	v_readfirstlane_b32 s3, v3
	v_sub_u32_e32 v3, 0, v2
	v_rcp_iflag_f32_e32 v4, v4
	v_add_u32_e32 v5, s3, v1
	v_mul_f32_e32 v4, 0x4f7ffffe, v4
	v_cvt_u32_f32_e32 v4, v4
	v_mul_lo_u32 v1, v3, v4
	v_mul_hi_u32 v1, v4, v1
	v_add_u32_e32 v1, v4, v1
	v_mul_hi_u32 v1, v5, v1
	v_mul_lo_u32 v3, v1, v2
	v_sub_u32_e32 v3, v5, v3
	v_add_u32_e32 v4, 1, v1
	v_cmp_ge_u32_e32 vcc, v3, v2
	s_nop 1
	v_cndmask_b32_e32 v1, v1, v4, vcc
	v_sub_u32_e32 v4, v3, v2
	v_cndmask_b32_e32 v3, v3, v4, vcc
	v_add_u32_e32 v4, 1, v1
	v_cmp_ge_u32_e32 vcc, v3, v2
	v_add_u32_e32 v3, 1, v5
	s_nop 0
	v_cndmask_b32_e32 v1, v1, v4, vcc
	v_mul_lo_u32 v4, v2, v1
	v_add_u32_e32 v2, v4, v2
	v_cmp_ne_u32_e32 vcc, v3, v2
	s_and_saveexec_b64 s[12:13], vcc
	s_xor_b64 s[12:13], exec, s[12:13]
	s_cbranch_execz .Lseam1_342
	v_add_u32_e32 v19, 2, v3
	v_cmp_eq_u32_e32 vcc, v19, v2
	s_cbranch_vccz .Lpf2_0
	buffer_wbl2 sc1

; __device__ __forceinline__ unsigned xb_ld(unsigned* p)              { return __hip_atomic_load(p, __ATOMIC_RELAXED, __HIP_MEMORY_SCOPE_AGENT); }
; __device__ __forceinline__ unsigned xb_add(unsigned* p, unsigned v) { return __hip_atomic_fetch_add(p, v, __ATOMIC_RELAXED, __HIP_MEMORY_SCOPE_AGENT); }
; #define XB_SPIN(cond, bar) do { unsigned _sp = 0; while (cond) { __builtin_amdgcn_s_sleep(1); \
;     if ((++_sp & 255u) == 0u) { if (xb_ld(&(bar)[XB_TMO])) break; if (_sp > XB_SPIN_CAP) { atomicAdd(&(bar)[XB_TMO], 1u); break; } } } } while (0)
; __device__ __forceinline__ void xcd_barrier(const XcdBarrier& b, const int wv) {
;     ...
;         unsigned nloc = b.st[0], nx = b.st[1];
;         if (nloc == 0u) { xcd_barrier_complete(bar, b.x, nloc, nx); b.st[0] = nloc; b.st[1] = nx; }
;         const unsigned old = xb_add(&bar[XB_XSUB(b.x)], 1u);
;         const unsigned gen = old / nloc;
;         if (old + 1u == (gen + 1u) * nloc) {
;             __builtin_amdgcn_fence(__ATOMIC_RELEASE, "agent");
;             asm volatile("s_waitcnt vmcnt(0)" ::: "memory");
;             const unsigned og = xb_add(&bar[XB_TOP], 1u);
;             const unsigned tg = og / nx;
;             if (og + 1u == (tg + 1u) * nx) xb_add(&bar[XB_TOPGEN], 1u);
;             else XB_SPIN(xb_ld(&bar[XB_TOPGEN]) == tg, bar);
.LBB0_727:
	s_or_b64 exec, exec, s[16:17]
	v_cvt_f32_u32_e32 v4, v2
	s_waitcnt vmcnt(0)
	v_readfirstlane_b32 s3, v3
	v_sub_u32_e32 v3, 0, v2
	v_rcp_iflag_f32_e32 v4, v4
	v_add_u32_e32 v5, s3, v1
	v_mul_f32_e32 v4, 0x4f7ffffe, v4
	v_cvt_u32_f32_e32 v4, v4
	v_mul_lo_u32 v1, v3, v4
	v_mul_hi_u32 v1, v4, v1
	v_add_u32_e32 v1, v4, v1
	v_mul_hi_u32 v1, v5, v1
	v_mul_lo_u32 v3, v1, v2
	v_sub_u32_e32 v3, v5, v3
	v_add_u32_e32 v4, 1, v1
	v_cmp_ge_u32_e32 vcc, v3, v2
	s_nop 1
	v_cndmask_b32_e32 v1, v1, v4, vcc
	v_sub_u32_e32 v4, v3, v2
	v_cndmask_b32_e32 v3, v3, v4, vcc
	v_add_u32_e32 v4, 1, v1
	v_cmp_ge_u32_e32 vcc, v3, v2
	v_add_u32_e32 v3, 1, v5
	s_nop 0
	v_cndmask_b32_e32 v1, v1, v4, vcc
	v_mul_lo_u32 v4, v2, v1
	v_add_u32_e32 v2, v4, v2
	v_cmp_ne_u32_e32 vcc, v3, v2
	s_and_saveexec_b64 s[14:15], vcc
	s_xor_b64 s[14:15], exec, s[14:15]
	s_cbranch_execz .LBB0_741
	v_add_u32_e32 v19, 2, v3
	v_cmp_eq_u32_e32 vcc, v19, v2
	s_cbranch_vccz .Lpf2_4
	buffer_wbl2 sc1

; __device__ __forceinline__ unsigned xb_ld(unsigned* p)              { return __hip_atomic_load(p, __ATOMIC_RELAXED, __HIP_MEMORY_SCOPE_AGENT); }
; __device__ __forceinline__ unsigned xb_add(unsigned* p, unsigned v) { return __hip_atomic_fetch_add(p, v, __ATOMIC_RELAXED, __HIP_MEMORY_SCOPE_AGENT); }
; #define XB_SPIN(cond, bar) do { unsigned _sp = 0; while (cond) { __builtin_amdgcn_s_sleep(1); \
;     if ((++_sp & 255u) == 0u) { if (xb_ld(&(bar)[XB_TMO])) break; if (_sp > XB_SPIN_CAP) { atomicAdd(&(bar)[XB_TMO], 1u); break; } } } } while (0)
; __device__ __forceinline__ void xcd_barrier(const XcdBarrier& b, const int wv) {
;     ...
;         unsigned nloc = b.st[0], nx = b.st[1];
;         if (nloc == 0u) { xcd_barrier_complete(bar, b.x, nloc, nx); b.st[0] = nloc; b.st[1] = nx; }
;         const unsigned old = xb_add(&bar[XB_XSUB(b.x)], 1u);
;         const unsigned gen = old / nloc;
;         if (old + 1u == (gen + 1u) * nloc) {
;             __builtin_amdgcn_fence(__ATOMIC_RELEASE, "agent");
;             asm volatile("s_waitcnt vmcnt(0)" ::: "memory");
;             const unsigned og = xb_add(&bar[XB_TOP], 1u);
;             const unsigned tg = og / nx;
;             if (og + 1u == (tg + 1u) * nx) xb_add(&bar[XB_TOPGEN], 1u);
;             else XB_SPIN(xb_ld(&bar[XB_TOPGEN]) == tg, bar);
.LBB0_860:
	s_or_b64 exec, exec, s[18:19]
	v_cvt_f32_u32_e32 v4, v2
	s_waitcnt vmcnt(0)
	v_readfirstlane_b32 s3, v3
	v_sub_u32_e32 v3, 0, v2
	v_rcp_iflag_f32_e32 v4, v4
	v_add_u32_e32 v5, s3, v1
	v_mul_f32_e32 v4, 0x4f7ffffe, v4
	v_cvt_u32_f32_e32 v4, v4
	v_mul_lo_u32 v1, v3, v4
	v_mul_hi_u32 v1, v4, v1
	v_add_u32_e32 v1, v4, v1
	v_mul_hi_u32 v1, v5, v1
	v_mul_lo_u32 v3, v1, v2
	v_sub_u32_e32 v3, v5, v3
	v_add_u32_e32 v4, 1, v1
	v_cmp_ge_u32_e32 vcc, v3, v2
	s_nop 1
	v_cndmask_b32_e32 v1, v1, v4, vcc
	v_sub_u32_e32 v4, v3, v2
	v_cndmask_b32_e32 v3, v3, v4, vcc
	v_add_u32_e32 v4, 1, v1
	v_cmp_ge_u32_e32 vcc, v3, v2
	v_add_u32_e32 v3, 1, v5
	s_nop 0
	v_cndmask_b32_e32 v1, v1, v4, vcc
	v_mul_lo_u32 v4, v2, v1
	v_add_u32_e32 v2, v4, v2
	v_cmp_ne_u32_e32 vcc, v3, v2
	s_and_saveexec_b64 s[16:17], vcc
	s_xor_b64 s[16:17], exec, s[16:17]
	s_cbranch_execz .LBB0_874
	v_add_u32_e32 v19, 2, v3
	v_cmp_eq_u32_e32 vcc, v19, v2
	s_cbranch_vccz .Lpf2_6
	buffer_wbl2 sc1
